# first DFT pass: tile loads of the read-once mixer input tagged nt
# baseline (speedup 1.0000x reference)
; #define DFT1_ISSUE(zz, uu) do { const int dc_ = (uu) & 7, s2_ = ((uu) >> 3) & 63, b_ = (uu) >> 9; const bf16_t* src_ = Z + ((size_t)b_ * SEQ + s2_) * 512 + dc_ * 64; \
;         _Pragma("unroll") for (int i_ = 0; i_ < 2; ++i_) { const int ci_ = tid + 512 * i_; pf[zz][i_] = *(const u32x4*)(src_ + (size_t)(ci_ >> 3) * (64 * 512) + (ci_ & 7) * 8); } } while (0)
; __device__ __forceinline__ void dft1_phase(const Args& a, LAS unsigned char* lds, int tid, int lane, int wave) {
;     ...
;     const int G2 = 2 * (int)gridDim.x;
;     { const int u0 = blockIdx.x; if (u0 < 4096) DFT1_ISSUE(0, u0); if (u0 + (int)gridDim.x < 4096) DFT1_ISSUE(1, u0 + (int)gridDim.x); }
.LBB0_286:
	v_mov_b32_e32 v3, v186
	v_mov_b32_e32 v2, v178
	s_and_b64 vcc, exec, s[64:65]
	v_lshlrev_b32_e32 v4, 4, v2
	v_ashrrev_i32_e32 v0, 3, v2
	s_cbranch_vccz .LBB0_288
	s_ashr_i32 s0, s2, 9
	s_ashr_i32 s1, s0, 31
	s_lshl_b64 s[0:1], s[0:1], 23
	s_add_u32 s0, s38, s0
	s_addc_u32 s1, s39, s1
	s_lshl_b32 s4, s2, 7
	s_and_b32 s5, s4, 0xfc00
	s_add_u32 s0, s0, s5
	s_addc_u32 s1, s1, 0
	s_and_b32 s4, s4, 0x380
	v_ashrrev_i32_e32 v1, 31, v0
	s_add_u32 s0, s0, s4
	v_lshlrev_b64 v[8:9], 16, v[0:1]
	v_add_u32_e32 v1, 0x200, v2
	s_addc_u32 s1, s1, 0
	v_and_b32_e32 v6, 0x70, v4
	v_mov_b32_e32 v7, 0
	v_ashrrev_i32_e32 v10, 3, v1
	v_lshl_add_u64 v[6:7], s[0:1], 0, v[6:7]
	v_ashrrev_i32_e32 v11, 31, v10
	v_lshl_add_u64 v[8:9], v[6:7], 0, v[8:9]
	v_lshlrev_b64 v[10:11], 16, v[10:11]
	v_lshl_add_u64 v[6:7], v[6:7], 0, v[10:11]
	global_load_dwordx4 v[32:35], v[8:9], off nt
	global_load_dwordx4 v[36:39], v[6:7], off nt
.LBB0_288:
	s_add_i32 s0, s54, s2
	s_cmpk_gt_i32 s0, 0xfff
	s_cbranch_scc1 .LBB0_290
	s_ashr_i32 s4, s0, 9
	s_ashr_i32 s5, s4, 31
	s_lshl_b64 s[4:5], s[4:5], 23
	s_add_u32 s1, s38, s4
	s_addc_u32 s4, s39, s5
	s_lshl_b32 s0, s0, 7
	s_and_b32 s5, s0, 0xfc00
	s_add_u32 s1, s1, s5
	s_addc_u32 s4, s4, 0
	s_and_b32 s0, s0, 0x380
	v_ashrrev_i32_e32 v1, 31, v0
	s_add_u32 s0, s1, s0
	v_lshlrev_b64 v[8:9], 16, v[0:1]
	v_add_u32_e32 v1, 0x200, v2
	s_addc_u32 s1, s4, 0
	v_and_b32_e32 v6, 0x70, v4
	v_mov_b32_e32 v7, 0
	v_ashrrev_i32_e32 v10, 3, v1
	v_lshl_add_u64 v[6:7], s[0:1], 0, v[6:7]
	v_ashrrev_i32_e32 v11, 31, v10
	v_lshl_add_u64 v[8:9], v[6:7], 0, v[8:9]
	v_lshlrev_b64 v[10:11], 16, v[10:11]
	v_lshl_add_u64 v[6:7], v[6:7], 0, v[10:11]
	global_load_dwordx4 v[40:43], v[8:9], off nt
	global_load_dwordx4 v[44:47], v[6:7], off nt
	s_lshr_b32 s90, s86, 8
	s_andn2_b64 vcc, exec, s[64:65]
	s_lshl_b32 s89, s90, 6
	s_cbranch_vccnz .LBB0_327
	s_branch .LBB0_291

; #define LAS __attribute__((address_space(3)))
; #define DFT1_ISSUE(zz, uu) do { const int dc_ = (uu) & 7, s2_ = ((uu) >> 3) & 63, b_ = (uu) >> 9; const bf16_t* src_ = Z + ((size_t)b_ * SEQ + s2_) * 512 + dc_ * 64; \
;         _Pragma("unroll") for (int i_ = 0; i_ < 2; ++i_) { const int ci_ = tid + 512 * i_; pf[zz][i_] = *(const u32x4*)(src_ + (size_t)(ci_ >> 3) * (64 * 512) + (ci_ & 7) * 8); } } while (0)
; __device__ __forceinline__ void dft1_phase(const Args& a, LAS unsigned char* lds, int tid, int lane, int wave) {
;     ...
;     for (int u = blockIdx.x; u < 4096; u += G2) {
;         const bool has1 = u + (int)gridDim.x < 4096;
; #pragma unroll
;         for (int z = 0; z < 2; ++z)
; #pragma unroll
;             for (int i = 0; i < 2; ++i) { const int ci = tid + 512 * i; *(LAS u32x4*)(lds + z * 24576 + (ci >> 3) * TP + (ci & 7) * 16) = pf[z][i]; }
;         __syncthreads();
;         { const int un = u + G2; if (un < 4096) DFT1_ISSUE(0, un); if (un + (int)gridDim.x < 4096) DFT1_ISSUE(1, un + (int)gridDim.x); }
.LBB0_294:
	s_add_i32 s10, s14, s20
	s_cmpk_gt_i32 s10, 0xfff
	s_waitcnt vmcnt(1)
	ds_write_b128 v119, v[32:35]
	s_waitcnt vmcnt(0)
	ds_write_b128 v120, v[36:39]
	ds_write_b128 v119, v[40:43] offset:24576
	ds_write_b128 v120, v[44:47] offset:24576
	s_waitcnt lgkmcnt(0)
	s_barrier
	s_cbranch_scc1 .LBB0_296
	s_ashr_i32 s10, s10, 9
	s_ashr_i32 s11, s10, 31
	s_add_i32 s21, s13, s12
	s_and_b32 s22, s21, 0x7e00
	s_lshl_b64 s[10:11], s[10:11], 23
	s_add_u32 s10, s38, s10
	s_addc_u32 s11, s39, s11
	s_lshl_b32 s22, s22, 1
	s_add_u32 s10, s10, s22
	s_addc_u32 s11, s11, 0
	s_and_b32 s21, s21, 0x1c0
	s_lshl_b32 s21, s21, 1
	s_add_u32 s10, s10, s21
	s_addc_u32 s11, s11, 0
	v_lshl_add_u64 v[0:1], s[10:11], 0, v[80:81]
	v_lshl_add_u64 v[2:3], v[0:1], 0, v[82:83]
	v_lshl_add_u64 v[0:1], v[0:1], 0, v[84:85]
	global_load_dwordx4 v[32:35], v[2:3], off nt
	global_load_dwordx4 v[36:39], v[0:1], off nt
.LBB0_296:
	s_add_i32 s10, s15, s20
	s_cmpk_gt_i32 s10, 0xfff
	s_cbranch_scc1 .LBB0_298
	s_ashr_i32 s10, s10, 9
	s_ashr_i32 s11, s10, 31
	s_add_i32 s21, s16, s12
	s_and_b32 s22, s21, 0x7e00
	s_lshl_b64 s[10:11], s[10:11], 23
	s_add_u32 s10, s38, s10
	s_addc_u32 s11, s39, s11
	s_lshl_b32 s22, s22, 1
	s_add_u32 s10, s10, s22
	s_addc_u32 s11, s11, 0
	s_and_b32 s21, s21, 0x1c0
	s_lshl_b32 s21, s21, 1
	s_add_u32 s10, s10, s21
	s_addc_u32 s11, s11, 0
	v_lshl_add_u64 v[0:1], s[10:11], 0, v[80:81]
	v_lshl_add_u64 v[2:3], v[0:1], 0, v[82:83]
	v_lshl_add_u64 v[0:1], v[0:1], 0, v[84:85]
	global_load_dwordx4 v[40:43], v[2:3], off nt
	global_load_dwordx4 v[44:47], v[0:1], off nt
